# grid barrier: the per-XCD relay word is no longer incremented by the XCD's last arrival (nobody waits on it any more), removing one atomic round trip from that path
# baseline (speedup 1.0000x reference)
.LBB0_209:
	s_or_b64 exec, exec, s[2:3]
	s_mov_b64 s[2:3], exec
	v_mbcnt_lo_u32_b32 v0, s2, 0
	v_mbcnt_hi_u32_b32 v0, s3, v0
	v_cmp_eq_u32_e32 vcc, 0, v0
	s_waitcnt vmcnt(0)
	buffer_inv sc1
	s_and_saveexec_b64 s[6:7], vcc
	s_cbranch_execz .LBB0_211
	s_bcnt1_i32_b64 s2, s[2:3]
	v_mov_b32_e32 v0, 0x2000
	v_mov_b32_e32 v1, s2
.LBB0_211:
	s_or_b64 exec, exec, s[6:7]
	s_waitcnt vmcnt(0)

.LBB0_366:
	s_or_b64 exec, exec, s[0:1]
	s_mov_b64 s[0:1], exec
	v_mbcnt_lo_u32_b32 v0, s0, 0
	v_mbcnt_hi_u32_b32 v0, s1, v0
	v_cmp_eq_u32_e32 vcc, 0, v0
	s_waitcnt vmcnt(0)
	buffer_inv sc1
	s_and_saveexec_b64 s[2:3], vcc
	s_cbranch_execz .LBB0_368
	s_bcnt1_i32_b64 s0, s[0:1]
	v_mov_b32_e32 v0, 0x2000
	v_mov_b32_e32 v1, s0
.LBB0_368:
	s_or_b64 exec, exec, s[2:3]
	s_waitcnt vmcnt(0)

.LBB0_489:
	s_or_b64 exec, exec, s[0:1]
	s_mov_b64 s[0:1], exec
	v_mbcnt_lo_u32_b32 v0, s0, 0
	v_mbcnt_hi_u32_b32 v0, s1, v0
	v_cmp_eq_u32_e32 vcc, 0, v0
	s_waitcnt vmcnt(0)
	buffer_inv sc1
	s_and_saveexec_b64 s[2:3], vcc
	s_cbranch_execz .LBB0_491
	s_bcnt1_i32_b64 s0, s[0:1]
	v_mov_b32_e32 v0, 0x2000
	v_mov_b32_e32 v1, s0
.LBB0_491:
	s_or_b64 exec, exec, s[2:3]
	s_waitcnt vmcnt(0)

.LBB0_688:
	s_or_b64 exec, exec, s[2:3]
	s_mov_b64 s[2:3], exec
	v_mbcnt_lo_u32_b32 v0, s2, 0
	v_mbcnt_hi_u32_b32 v0, s3, v0
	v_cmp_eq_u32_e32 vcc, 0, v0
	s_waitcnt vmcnt(0)
	buffer_inv sc1
	s_and_saveexec_b64 s[6:7], vcc
	s_cbranch_execz .LBB0_690
	s_bcnt1_i32_b64 s2, s[2:3]
	v_mov_b32_e32 v0, 0x2000
	v_mov_b32_e32 v1, s2
.LBB0_690:
	s_or_b64 exec, exec, s[6:7]
	s_waitcnt vmcnt(0)

.LBB0_811:
	s_or_b64 exec, exec, s[0:1]
	s_mov_b64 s[0:1], exec
	v_mbcnt_lo_u32_b32 v0, s0, 0
	v_mbcnt_hi_u32_b32 v0, s1, v0
	v_cmp_eq_u32_e32 vcc, 0, v0
	s_waitcnt vmcnt(0)
	buffer_inv sc1
	s_and_saveexec_b64 s[2:3], vcc
	s_cbranch_execz .LBB0_813
	s_bcnt1_i32_b64 s0, s[0:1]
	v_mov_b32_e32 v0, 0x2000
	v_mov_b32_e32 v1, s0
.LBB0_813:
	s_or_b64 exec, exec, s[2:3]
	s_waitcnt vmcnt(0)

.LBB0_904:
	s_or_b64 exec, exec, s[2:3]
	s_mov_b64 s[2:3], exec
	v_mbcnt_lo_u32_b32 v0, s2, 0
	v_mbcnt_hi_u32_b32 v0, s3, v0
	v_cmp_eq_u32_e32 vcc, 0, v0
	s_waitcnt vmcnt(0)
	buffer_inv sc1
	s_and_saveexec_b64 s[6:7], vcc
	s_cbranch_execz .LBB0_906
	s_bcnt1_i32_b64 s2, s[2:3]
	v_mov_b32_e32 v0, 0x2000
	v_mov_b32_e32 v1, s2
.LBB0_906:
	s_or_b64 exec, exec, s[6:7]
	s_waitcnt vmcnt(0)

.LBB0_1014:
	s_or_b64 exec, exec, s[0:1]
	s_mov_b64 s[0:1], exec
	v_mbcnt_lo_u32_b32 v0, s0, 0
	v_mbcnt_hi_u32_b32 v0, s1, v0
	v_cmp_eq_u32_e32 vcc, 0, v0
	s_waitcnt vmcnt(0)
	buffer_inv sc1
	s_and_saveexec_b64 s[2:3], vcc
	s_cbranch_execz .LBB0_1016
	s_bcnt1_i32_b64 s0, s[0:1]
	v_mov_b32_e32 v0, s0
.LBB0_1016:
	s_or_b64 exec, exec, s[2:3]
	s_waitcnt vmcnt(0)

.LBB0_1110:
	s_or_b64 exec, exec, s[2:3]
	s_mov_b64 s[0:1], exec
	v_mbcnt_lo_u32_b32 v0, s0, 0
	v_mbcnt_hi_u32_b32 v0, s1, v0
	v_cmp_eq_u32_e32 vcc, 0, v0
	s_waitcnt vmcnt(0)
	buffer_inv sc1
	s_and_saveexec_b64 s[2:3], vcc
	s_cbranch_execz .LBB0_1112
	s_bcnt1_i32_b64 s0, s[0:1]
	v_mov_b32_e32 v0, s0
.LBB0_1112:
	s_or_b64 exec, exec, s[2:3]
	s_waitcnt vmcnt(0)

.LBB0_1443:
	s_or_b64 exec, exec, s[0:1]
	s_mov_b64 s[0:1], exec
	v_mbcnt_lo_u32_b32 v0, s0, 0
	v_mbcnt_hi_u32_b32 v0, s1, v0
	v_cmp_eq_u32_e32 vcc, 0, v0
	s_waitcnt vmcnt(0)
	buffer_inv sc1
	s_and_saveexec_b64 s[2:3], vcc
	s_cbranch_execz .LBB0_1445
	s_bcnt1_i32_b64 s0, s[0:1]
	v_mov_b32_e32 v0, s0
.LBB0_1445:
	s_or_b64 exec, exec, s[2:3]
	s_waitcnt vmcnt(0)

.LBB0_1505:
	s_or_b64 exec, exec, s[0:1]
	s_mov_b64 s[0:1], exec
	v_mbcnt_lo_u32_b32 v0, s0, 0
	v_mbcnt_hi_u32_b32 v0, s1, v0
	v_cmp_eq_u32_e32 vcc, 0, v0
	s_waitcnt vmcnt(0)
	buffer_inv sc1
	s_and_saveexec_b64 s[2:3], vcc
	s_cbranch_execz .LBB0_1507
	s_bcnt1_i32_b64 s0, s[0:1]
	v_mov_b32_e32 v0, s0
.LBB0_1507:
	s_or_b64 exec, exec, s[2:3]
	s_waitcnt vmcnt(0)

.LBB0_1579:
	s_or_b64 exec, exec, s[0:1]
	s_mov_b64 s[0:1], exec
	v_mbcnt_lo_u32_b32 v0, s0, 0
	v_mbcnt_hi_u32_b32 v0, s1, v0
	v_cmp_eq_u32_e32 vcc, 0, v0
	s_waitcnt vmcnt(0)
	buffer_inv sc1
	s_and_saveexec_b64 s[2:3], vcc
	s_cbranch_execz .LBB0_1581
	s_bcnt1_i32_b64 s0, s[0:1]
	v_mov_b32_e32 v0, s0
.LBB0_1581:
	s_or_b64 exec, exec, s[2:3]
	s_waitcnt vmcnt(0)

.LBB0_1670:
	s_or_b64 exec, exec, s[0:1]
	s_mov_b64 s[0:1], exec
	v_mbcnt_lo_u32_b32 v0, s0, 0
	v_mbcnt_hi_u32_b32 v0, s1, v0
	v_cmp_eq_u32_e32 vcc, 0, v0
	s_waitcnt vmcnt(0)
	buffer_inv sc1
	s_and_saveexec_b64 s[2:3], vcc
	s_cbranch_execz .LBB0_1672
	s_bcnt1_i32_b64 s0, s[0:1]
	v_mov_b32_e32 v0, s0
.LBB0_1672:
	s_or_b64 exec, exec, s[2:3]
	s_waitcnt vmcnt(0)

.LBB0_1805:
	s_or_b64 exec, exec, s[2:3]
	s_mov_b64 s[0:1], exec
	v_mbcnt_lo_u32_b32 v0, s0, 0
	v_mbcnt_hi_u32_b32 v0, s1, v0
	v_cmp_eq_u32_e32 vcc, 0, v0
	s_waitcnt vmcnt(0)
	buffer_inv sc1
	s_and_saveexec_b64 s[2:3], vcc
	s_cbranch_execz .LBB0_1807
	s_bcnt1_i32_b64 s0, s[0:1]
	v_mov_b32_e32 v0, s0
.LBB0_1807:
	s_or_b64 exec, exec, s[2:3]
	s_waitcnt vmcnt(0)

.LBB0_1900:
	s_or_b64 exec, exec, s[2:3]
	s_mov_b64 s[0:1], exec
	v_mbcnt_lo_u32_b32 v0, s0, 0
	v_mbcnt_hi_u32_b32 v0, s1, v0
	v_cmp_eq_u32_e32 vcc, 0, v0
	s_waitcnt vmcnt(0)
	buffer_inv sc1
	s_and_saveexec_b64 s[2:3], vcc
	s_cbranch_execz .LBB0_1902
	s_bcnt1_i32_b64 s0, s[0:1]
	v_mov_b32_e32 v0, s0
.LBB0_1902:
	s_or_b64 exec, exec, s[2:3]
	s_waitcnt vmcnt(0)

.LBB0_1973:
	s_or_b64 exec, exec, s[2:3]
	s_mov_b64 s[0:1], exec
	v_mbcnt_lo_u32_b32 v0, s0, 0
	v_mbcnt_hi_u32_b32 v0, s1, v0
	v_cmp_eq_u32_e32 vcc, 0, v0
	s_waitcnt vmcnt(0) lgkmcnt(0)
	buffer_inv sc1
	s_and_saveexec_b64 s[2:3], vcc
	s_cbranch_execz .LBB0_1975
	s_bcnt1_i32_b64 s0, s[0:1]
	v_mov_b32_e32 v0, s0
.LBB0_1975:
	s_or_b64 exec, exec, s[2:3]
	s_waitcnt vmcnt(0)

.LBB0_2102:
	s_or_b64 exec, exec, s[2:3]
	s_mov_b64 s[0:1], exec
	v_mbcnt_lo_u32_b32 v0, s0, 0
	v_mbcnt_hi_u32_b32 v0, s1, v0
	v_cmp_eq_u32_e32 vcc, 0, v0
	s_waitcnt vmcnt(0)
	buffer_inv sc1
	s_and_saveexec_b64 s[2:3], vcc
	s_cbranch_execz .LBB0_2104
	s_bcnt1_i32_b64 s0, s[0:1]
	v_mov_b32_e32 v0, s0
.LBB0_2104:
	s_or_b64 exec, exec, s[2:3]
	s_waitcnt vmcnt(0)

.LBB0_2165:
	s_or_b64 exec, exec, s[2:3]
	s_mov_b64 s[2:3], exec
	v_mbcnt_lo_u32_b32 v0, s2, 0
	v_mbcnt_hi_u32_b32 v0, s3, v0
	v_cmp_eq_u32_e32 vcc, 0, v0
	s_waitcnt vmcnt(0)
	buffer_inv sc1
	s_and_saveexec_b64 s[6:7], vcc
	s_cbranch_execz .LBB0_2167
	s_bcnt1_i32_b64 s2, s[2:3]
	v_mov_b32_e32 v0, 0x2000
	v_mov_b32_e32 v1, s2
.LBB0_2167:
	s_or_b64 exec, exec, s[6:7]
	s_waitcnt vmcnt(0)
